# phase 3 weight conversion: f32 weight reads (read once) marked nt so they do not evict the scan records from the cache hierarchy
# speedup vs baseline: 1.0048x; 1.0048x over previous
; #define LAS __attribute__((address_space(3)))
; DI unsigned pk2(float lo, float hi) { const f32x2_t v = {lo, hi}; return __builtin_bit_cast(unsigned, __builtin_convertvector(v, bf16x2_t)); }
; DI void transpose_item(const float* W, int K, int Nsrc, int srccol, int nvalid, const float* ksc, bf16_t* WT, int dstrow, int k0, LAS float* scr, int lane) {
;     f32x4 v[8];
; #pragma unroll
;     for (int i = 0; i < 8; ++i) { const int kk = k0 + 8 * i + (lane >> 3);
;         v[i] = (4 * (lane & 7) < nvalid) ? *(const f32x4*)(W + (size_t)kk * Nsrc + srccol + 4 * (lane & 7)) : (f32x4){0.f, 0.f, 0.f, 0.f};
;         if (ksc) v[i] = v[i] * ksc[kk]; }
; #pragma unroll
;     for (int i = 0; i < 8; ++i) { LAS float* d = scr + (8 * i + (lane >> 3)) * 33 + 4 * (lane & 7); d[0] = v[i].x; d[1] = v[i].y; d[2] = v[i].z; d[3] = v[i].w; }
;     asm volatile("s_waitcnt lgkmcnt(0)" ::: "memory");
;     const int c = lane & 7;
; #pragma unroll
;     for (int j = 0; j < 4; ++j) { const int n = (lane >> 3) + 8 * j; const LAS float* s = scr + (8 * c) * 33 + n;
;         u32x4 o; o.x = pk2(s[0 * 33], s[1 * 33]); o.y = pk2(s[2 * 33], s[3 * 33]); o.z = pk2(s[4 * 33], s[5 * 33]); o.w = pk2(s[6 * 33], s[7 * 33]);
;         *(u32x4*)(WT + (size_t)(dstrow + n) * K + k0 + 8 * c) = o; }
;     asm volatile("s_waitcnt lgkmcnt(0)" ::: "memory");
; }
; DI void convert_weights(const Args& a, int l, int sets, bf16_t* dstWin, int gw, int NGW, LAS unsigned char* lds, const int tidx) {
;     ...
;             { const int nblk = DM / 32, kb = r / nblk, nb = r % nblk; transpose_item(wdn, DFF, DM, 32 * nb, 32, nullptr, WdnT, 32 * nb, 64 * kb, scr, lane); }
.LBB0_269:
	s_movk_i32 s0, 0x7ff
	v_cmp_lt_i32_e32 vcc, s0, v44
	s_and_saveexec_b64 s[0:1], vcc
	s_xor_b64 s[10:11], exec, s[0:1]
	s_cbranch_execz .LBB0_291
	s_movk_i32 s0, 0x27ff
	v_cmp_lt_u32_e32 vcc, s0, v44
	s_and_saveexec_b64 s[0:1], vcc
	s_xor_b64 s[0:1], exec, s[0:1]
	s_cbranch_execz .LBB0_272
	v_and_b32_e32 v0, 0x7fffffc0, v44
	v_add_u32_e32 v0, 0xffffd800, v0
	v_and_b32_e32 v2, 0x7e0, v52
	v_or_b32_e32 v54, v0, v45
	v_lshlrev_b32_e32 v204, 2, v2
	s_waitcnt vmcnt(0)
	v_lshl_add_u64 v[56:57], v[32:33], 0, v[204:205]
	v_mov_b32_e32 v55, v205
	v_or_b32_e32 v204, 8, v54
	v_lshlrev_b64 v[4:5], 13, v[54:55]
	v_lshlrev_b64 v[8:9], 13, v[204:205]
	v_lshl_add_u64 v[4:5], v[56:57], 0, v[4:5]
	v_lshl_add_u64 v[8:9], v[56:57], 0, v[8:9]
	v_or_b32_e32 v204, 16, v54
	global_load_dwordx4 v[4:7], v[4:5], off nt
	v_lshlrev_b64 v[12:13], 13, v[204:205]
	global_load_dwordx4 v[8:11], v[8:9], off nt
	v_lshl_add_u64 v[12:13], v[56:57], 0, v[12:13]
	v_or_b32_e32 v204, 24, v54
	global_load_dwordx4 v[12:15], v[12:13], off nt
	v_lshlrev_b64 v[16:17], 13, v[204:205]
	v_lshl_add_u64 v[16:17], v[56:57], 0, v[16:17]
	v_or_b32_e32 v204, 32, v54
	global_load_dwordx4 v[16:19], v[16:17], off nt
	v_lshlrev_b64 v[20:21], 13, v[204:205]
	v_lshl_add_u64 v[20:21], v[56:57], 0, v[20:21]
	v_or_b32_e32 v204, 40, v54
	global_load_dwordx4 v[20:23], v[20:21], off nt
	v_lshlrev_b64 v[24:25], 13, v[204:205]
	v_lshl_add_u64 v[24:25], v[56:57], 0, v[24:25]
	v_or_b32_e32 v204, 48, v54
	global_load_dwordx4 v[24:27], v[24:25], off nt
	v_lshlrev_b64 v[28:29], 13, v[204:205]
	v_lshl_add_u64 v[28:29], v[56:57], 0, v[28:29]
	v_or_b32_e32 v204, 56, v54
	global_load_dwordx4 v[28:31], v[28:29], off nt
	v_lshlrev_b64 v[54:55], 13, v[204:205]
	v_lshl_add_u64 v[54:55], v[56:57], 0, v[54:55]
	global_load_dwordx4 v[54:57], v[54:55], off nt
	v_add_u32_e32 v1, v46, v47
	v_add_u32_e32 v3, 0x420, v1
	s_waitcnt vmcnt(7)
	ds_write2_b32 v1, v4, v5 offset1:1
	ds_write2_b32 v1, v6, v7 offset0:2 offset1:3
	s_waitcnt vmcnt(6)
	ds_write2_b32 v3, v8, v9 offset1:1
	v_add_u32_e32 v3, 0x428, v1
	ds_write2_b32 v3, v10, v11 offset1:1
	v_add_u32_e32 v3, 0x840, v1
	s_waitcnt vmcnt(5)
	ds_write2_b32 v3, v12, v13 offset1:1
	v_add_u32_e32 v3, 0x848, v1
	ds_write2_b32 v3, v14, v15 offset1:1
	v_add_u32_e32 v3, 0xc60, v1
	s_waitcnt vmcnt(4)
	ds_write2_b32 v3, v16, v17 offset1:1
	v_add_u32_e32 v3, 0xc68, v1
	ds_write2_b32 v3, v18, v19 offset1:1
	v_add_u32_e32 v3, 0x1080, v1
	s_waitcnt vmcnt(3)
	ds_write2_b32 v3, v20, v21 offset1:1
	v_add_u32_e32 v3, 0x1088, v1
	ds_write2_b32 v3, v22, v23 offset1:1
	v_add_u32_e32 v3, 0x14a0, v1
	s_waitcnt vmcnt(2)
	ds_write2_b32 v3, v24, v25 offset1:1
	v_add_u32_e32 v3, 0x14a8, v1
	ds_write2_b32 v3, v26, v27 offset1:1
	v_add_u32_e32 v3, 0x18c0, v1
	s_waitcnt vmcnt(1)
	ds_write2_b32 v3, v28, v29 offset1:1
	v_add_u32_e32 v3, 0x18c8, v1
	ds_write2_b32 v3, v30, v31 offset1:1
	v_add_u32_e32 v3, 0x1ce0, v1
	v_add_u32_e32 v1, 0x1ce8, v1
	s_waitcnt vmcnt(0)
	ds_write2_b32 v3, v54, v55 offset1:1
	ds_write2_b32 v1, v56, v57 offset1:1
	s_waitcnt lgkmcnt(0)
	ds_read2_b32 v[8:9], v51 offset0:33 offset1:41
	ds_read2_b32 v[10:11], v51 offset1:8
	ds_read2_b32 v[12:13], v51 offset0:66 offset1:74
	ds_read2_b32 v[14:15], v51 offset0:99 offset1:107
	ds_read2_b32 v[16:17], v51 offset0:132 offset1:140
	ds_read2_b32 v[18:19], v51 offset0:165 offset1:173
	ds_read2_b32 v[20:21], v51 offset0:198 offset1:206
	ds_read2_b32 v[22:23], v51 offset0:231 offset1:239
	v_mov_b32_e32 v1, v205
	v_or_b32_e32 v3, v2, v45
	v_lshl_add_u64 v[0:1], v[0:1], 1, v[34:35]
	v_lshlrev_b32_e32 v204, 14, v3
	v_or_b32_e32 v3, v2, v48
	s_waitcnt lgkmcnt(6)
	v_cvt_pk_bf16_f32 v4, v10, v8
	s_waitcnt lgkmcnt(4)
	v_cvt_pk_bf16_f32 v5, v12, v14
	s_waitcnt lgkmcnt(2)
	v_cvt_pk_bf16_f32 v6, v16, v18
	s_waitcnt lgkmcnt(0)
	v_cvt_pk_bf16_f32 v7, v20, v22
	v_lshl_add_u64 v[24:25], v[0:1], 0, v[204:205]
	v_lshlrev_b32_e32 v204, 14, v3
	global_store_dwordx4 v[24:25], v[4:7], off
	v_or_b32_e32 v3, v2, v49
	v_or_b32_e32 v2, v2, v50
	v_cvt_pk_bf16_f32 v4, v11, v9
	v_cvt_pk_bf16_f32 v5, v13, v15
	v_cvt_pk_bf16_f32 v6, v17, v19
	v_cvt_pk_bf16_f32 v7, v21, v23
	v_lshl_add_u64 v[8:9], v[0:1], 0, v[204:205]
	global_store_dwordx4 v[8:9], v[4:7], off
	ds_read2_b32 v[8:9], v51 offset0:49 offset1:57
	ds_read2_b32 v[10:11], v51 offset0:16 offset1:24
	ds_read2_b32 v[12:13], v51 offset0:82 offset1:90
	ds_read2_b32 v[14:15], v51 offset0:115 offset1:123
	ds_read2_b32 v[16:17], v51 offset0:148 offset1:156
	ds_read2_b32 v[18:19], v51 offset0:181 offset1:189
	ds_read2_b32 v[20:21], v51 offset0:214 offset1:222
	ds_read2_b32 v[22:23], v51 offset0:247 offset1:255
	v_lshlrev_b32_e32 v204, 14, v3
	s_waitcnt lgkmcnt(6)
	v_cvt_pk_bf16_f32 v4, v10, v8
	s_waitcnt lgkmcnt(4)
	v_cvt_pk_bf16_f32 v5, v12, v14
	s_waitcnt lgkmcnt(2)
	v_cvt_pk_bf16_f32 v6, v16, v18
	s_waitcnt lgkmcnt(0)
	v_cvt_pk_bf16_f32 v7, v20, v22
	v_lshl_add_u64 v[24:25], v[0:1], 0, v[204:205]
	v_lshlrev_b32_e32 v204, 14, v2
	global_store_dwordx4 v[24:25], v[4:7], off
	v_lshl_add_u64 v[0:1], v[0:1], 0, v[204:205]
	s_nop 0
	v_cvt_pk_bf16_f32 v4, v11, v9
	v_cvt_pk_bf16_f32 v5, v13, v15
	v_cvt_pk_bf16_f32 v6, v17, v19
	v_cvt_pk_bf16_f32 v7, v21, v23
	global_store_dwordx4 v[0:1], v[4:7], off
	s_waitcnt lgkmcnt(0)
; #define LAS __attribute__((address_space(3)))
; DI void transpose_item(const float* W, int K, int Nsrc, int srccol, int nvalid, const float* ksc, bf16_t* WT, int dstrow, int k0, LAS float* scr, int lane) {
;     f32x4 v[8];
; #pragma unroll
;     for (int i = 0; i < 8; ++i) { const int kk = k0 + 8 * i + (lane >> 3);
;         v[i] = (4 * (lane & 7) < nvalid) ? *(const f32x4*)(W + (size_t)kk * Nsrc + srccol + 4 * (lane & 7)) : (f32x4){0.f, 0.f, 0.f, 0.f};
;         if (ksc) v[i] = v[i] * ksc[kk]; }
; DI void convert_weights(const Args& a, int l, int sets, bf16_t* dstWin, int gw, int NGW, LAS unsigned char* lds, const int tidx) {
;     ...
;             if (r < I_UP) { const int nblk = DFF / 32, kb = r / nblk, nb = r % nblk; transpose_item(wup, DM, DFF, 32 * nb, 32, a.norm2_w + l * DM, WupT, 32 * nb, 64 * kb, scr, lane); continue; } r -= I_UP;
.LBB0_272:
	s_andn2_saveexec_b64 s[12:13], s[0:1]
	s_cbranch_execz .LBB0_290
	v_add_u32_e32 v0, 0xfffff800, v44
	v_lshrrev_b32_e32 v0, 2, v0
	v_and_b32_e32 v53, 0x1fe0, v52
	v_and_b32_e32 v54, 0x3fffffc0, v0
	v_or_b32_e32 v0, v54, v45
	v_lshlrev_b32_e32 v204, 2, v53
	v_lshl_add_u64 v[28:29], v[36:37], 0, v[204:205]
	v_mov_b32_e32 v204, v0
	v_lshlrev_b64 v[0:1], 15, v[204:205]
	v_lshl_add_u64 v[0:1], v[28:29], 0, v[0:1]
	global_load_dwordx4 v[0:3], v[0:1], off nt
	v_readlane_b32 s16, v252, 22
	v_readlane_b32 s17, v252, 23
	s_andn2_b64 vcc, exec, s[16:17]
	v_lshlrev_b32_e32 v55, 2, v204
	v_cndmask_b32_e64 v4, 0, 1, s[16:17]
	v_cmp_ne_u32_e64 s[0:1], 1, v4
	s_cbranch_vccnz .LBB0_275
	global_load_dword v4, v55, s[6:7]
	s_waitcnt vmcnt(0)
	v_pk_mul_f32 v[2:3], v[2:3], v[4:5] op_sel_hi:[1,0]
	v_pk_mul_f32 v[0:1], v[0:1], v[4:5] op_sel_hi:[1,0]
.LBB0_275:
	v_or_b32_e32 v4, 8, v204
	v_mov_b32_e32 v5, v205
	v_lshlrev_b64 v[4:5], 15, v[4:5]
	v_lshl_add_u64 v[4:5], v[28:29], 0, v[4:5]
	global_load_dwordx4 v[4:7], v[4:5], off nt
	s_and_b64 vcc, exec, s[0:1]
	s_cbranch_vccnz .LBB0_277
	global_load_dword v8, v55, s[6:7] offset:32
	s_waitcnt vmcnt(0)
	v_pk_mul_f32 v[6:7], v[6:7], v[8:9] op_sel_hi:[1,0]
	v_pk_mul_f32 v[4:5], v[4:5], v[8:9] op_sel_hi:[1,0]
.LBB0_277:
	v_or_b32_e32 v8, 16, v204
	v_mov_b32_e32 v9, v205
	v_lshlrev_b64 v[8:9], 15, v[8:9]
	v_lshl_add_u64 v[8:9], v[28:29], 0, v[8:9]
	global_load_dwordx4 v[8:11], v[8:9], off nt
	s_and_b64 vcc, exec, s[0:1]
	s_cbranch_vccnz .LBB0_279
	global_load_dword v12, v55, s[6:7] offset:64
	s_waitcnt vmcnt(0)
	v_pk_mul_f32 v[10:11], v[10:11], v[12:13] op_sel_hi:[1,0]
	v_pk_mul_f32 v[8:9], v[8:9], v[12:13] op_sel_hi:[1,0]
.LBB0_279:
	v_or_b32_e32 v12, 24, v204
	v_mov_b32_e32 v13, v205
	v_lshlrev_b64 v[12:13], 15, v[12:13]
	v_lshl_add_u64 v[12:13], v[28:29], 0, v[12:13]
	global_load_dwordx4 v[12:15], v[12:13], off nt
	s_and_b64 vcc, exec, s[0:1]
	s_cbranch_vccnz .LBB0_281
	global_load_dword v16, v55, s[6:7] offset:96
	s_waitcnt vmcnt(0)
	v_pk_mul_f32 v[14:15], v[14:15], v[16:17] op_sel_hi:[1,0]
	v_pk_mul_f32 v[12:13], v[12:13], v[16:17] op_sel_hi:[1,0]
.LBB0_281:
	v_or_b32_e32 v16, 32, v204
	v_mov_b32_e32 v17, v205
	v_lshlrev_b64 v[16:17], 15, v[16:17]
	v_lshl_add_u64 v[16:17], v[28:29], 0, v[16:17]
	global_load_dwordx4 v[16:19], v[16:17], off nt
	s_and_b64 vcc, exec, s[0:1]
	s_cbranch_vccnz .LBB0_283
	global_load_dword v20, v55, s[6:7] offset:128
	s_waitcnt vmcnt(0)
	v_pk_mul_f32 v[18:19], v[18:19], v[20:21] op_sel_hi:[1,0]
	v_pk_mul_f32 v[16:17], v[16:17], v[20:21] op_sel_hi:[1,0]
.LBB0_283:
	v_or_b32_e32 v20, 40, v204
	v_mov_b32_e32 v21, v205
	v_lshlrev_b64 v[20:21], 15, v[20:21]
	v_lshl_add_u64 v[20:21], v[28:29], 0, v[20:21]
	global_load_dwordx4 v[20:23], v[20:21], off nt
	s_and_b64 vcc, exec, s[0:1]
	s_cbranch_vccnz .LBB0_285
	global_load_dword v24, v55, s[6:7] offset:160
	s_waitcnt vmcnt(0)
	v_pk_mul_f32 v[22:23], v[22:23], v[24:25] op_sel_hi:[1,0]
	v_pk_mul_f32 v[20:21], v[20:21], v[24:25] op_sel_hi:[1,0]
.LBB0_285:
	v_or_b32_e32 v24, 48, v204
	v_mov_b32_e32 v25, v205
	v_lshlrev_b64 v[24:25], 15, v[24:25]
	v_lshl_add_u64 v[24:25], v[28:29], 0, v[24:25]
	global_load_dwordx4 v[24:27], v[24:25], off nt
	s_and_b64 vcc, exec, s[0:1]
	s_cbranch_vccnz .LBB0_287
	global_load_dword v30, v55, s[6:7] offset:192
	s_waitcnt vmcnt(0)
	v_pk_mul_f32 v[26:27], v[26:27], v[30:31] op_sel_hi:[1,0]
	v_pk_mul_f32 v[24:25], v[24:25], v[30:31] op_sel_hi:[1,0]
.LBB0_287:
	v_or_b32_e32 v204, 56, v204
	v_lshlrev_b64 v[30:31], 15, v[204:205]
	v_lshl_add_u64 v[28:29], v[28:29], 0, v[30:31]
	global_load_dwordx4 v[28:31], v[28:29], off nt
	s_and_b64 vcc, exec, s[0:1]
	s_cbranch_vccnz .LBB0_289
	global_load_dword v56, v55, s[6:7] offset:224
	s_waitcnt vmcnt(0)
	v_pk_mul_f32 v[30:31], v[30:31], v[56:57] op_sel_hi:[1,0]
	v_pk_mul_f32 v[28:29], v[28:29], v[56:57] op_sel_hi:[1,0]

; #define LAS __attribute__((address_space(3)))
; DI unsigned pk2(float lo, float hi) { const f32x2_t v = {lo, hi}; return __builtin_bit_cast(unsigned, __builtin_convertvector(v, bf16x2_t)); }
; DI void transpose_item(const float* W, int K, int Nsrc, int srccol, int nvalid, const float* ksc, bf16_t* WT, int dstrow, int k0, LAS float* scr, int lane) {
;     f32x4 v[8];
; #pragma unroll
;     for (int i = 0; i < 8; ++i) { const int kk = k0 + 8 * i + (lane >> 3);
;         v[i] = (4 * (lane & 7) < nvalid) ? *(const f32x4*)(W + (size_t)kk * Nsrc + srccol + 4 * (lane & 7)) : (f32x4){0.f, 0.f, 0.f, 0.f};
;         if (ksc) v[i] = v[i] * ksc[kk]; }
; #pragma unroll
;     for (int i = 0; i < 8; ++i) { LAS float* d = scr + (8 * i + (lane >> 3)) * 33 + 4 * (lane & 7); d[0] = v[i].x; d[1] = v[i].y; d[2] = v[i].z; d[3] = v[i].w; }
;     asm volatile("s_waitcnt lgkmcnt(0)" ::: "memory");
;     const int c = lane & 7;
; #pragma unroll
;     for (int j = 0; j < 4; ++j) { const int n = (lane >> 3) + 8 * j; const LAS float* s = scr + (8 * c) * 33 + n;
;         u32x4 o; o.x = pk2(s[0 * 33], s[1 * 33]); o.y = pk2(s[2 * 33], s[3 * 33]); o.z = pk2(s[4 * 33], s[5 * 33]); o.w = pk2(s[6 * 33], s[7 * 33]);
;         *(u32x4*)(WT + (size_t)(dstrow + n) * K + k0 + 8 * c) = o; }
;     asm volatile("s_waitcnt lgkmcnt(0)" ::: "memory");
; }
; DI void convert_weights(const Args& a, int l, int sets, bf16_t* dstWin, int gw, int NGW, LAS unsigned char* lds, const int tidx) {
;     ...
;             if (r < I_OUT) { const int nblk = DM / 32, kb = r / nblk, nb = r % nblk; transpose_item(wout, DM, DM, 32 * nb, 32, nullptr, WoutT, 32 * nb, 64 * kb, scr, lane); continue; } r -= I_OUT;
.LBB0_291:
	s_andn2_saveexec_b64 s[0:1], s[10:11]
	s_cbranch_execz .LBB0_268
	v_ashrrev_i32_e32 v0, 31, v44
	v_lshrrev_b32_e32 v0, 26, v0
	v_add_u32_e32 v0, v44, v0
	v_lshlrev_b32_e32 v1, 5, v0
	v_and_b32_e32 v1, 0xfffff800, v1
	s_waitcnt vmcnt(0)
	v_and_b32_e32 v56, 0xffffffc0, v0
	v_sub_u32_e32 v54, v52, v1
	v_or_b32_e32 v28, v56, v45
	v_ashrrev_i32_e32 v55, 31, v54
	v_ashrrev_i32_e32 v29, 31, v28
	v_or_b32_e32 v4, 8, v28
	v_lshl_add_u64 v[30:31], v[54:55], 2, v[40:41]
	v_lshlrev_b64 v[0:1], 13, v[28:29]
	v_ashrrev_i32_e32 v5, 31, v4
	v_lshl_add_u64 v[0:1], v[30:31], 0, v[0:1]
	v_lshlrev_b64 v[4:5], 13, v[4:5]
	v_or_b32_e32 v8, 16, v28
	global_load_dwordx4 v[0:3], v[0:1], off nt
	v_lshl_add_u64 v[4:5], v[30:31], 0, v[4:5]
	v_ashrrev_i32_e32 v9, 31, v8
	global_load_dwordx4 v[4:7], v[4:5], off nt
	v_lshlrev_b64 v[8:9], 13, v[8:9]
	v_or_b32_e32 v12, 24, v28
	v_lshl_add_u64 v[8:9], v[30:31], 0, v[8:9]
	v_ashrrev_i32_e32 v13, 31, v12
	global_load_dwordx4 v[8:11], v[8:9], off nt
	v_lshlrev_b64 v[12:13], 13, v[12:13]
	v_or_b32_e32 v16, 32, v28
	v_lshl_add_u64 v[12:13], v[30:31], 0, v[12:13]
	v_ashrrev_i32_e32 v17, 31, v16
	global_load_dwordx4 v[12:15], v[12:13], off nt
	v_lshlrev_b64 v[16:17], 13, v[16:17]
	v_or_b32_e32 v20, 40, v28
	v_lshl_add_u64 v[16:17], v[30:31], 0, v[16:17]
	v_ashrrev_i32_e32 v21, 31, v20
	global_load_dwordx4 v[16:19], v[16:17], off nt
	v_lshlrev_b64 v[20:21], 13, v[20:21]
	v_or_b32_e32 v24, 48, v28
	v_lshl_add_u64 v[20:21], v[30:31], 0, v[20:21]
	v_ashrrev_i32_e32 v25, 31, v24
	global_load_dwordx4 v[20:23], v[20:21], off nt
	v_lshlrev_b64 v[24:25], 13, v[24:25]
	v_or_b32_e32 v28, 56, v28
	v_lshl_add_u64 v[24:25], v[30:31], 0, v[24:25]
	v_ashrrev_i32_e32 v29, 31, v28
	global_load_dwordx4 v[24:27], v[24:25], off nt
	v_lshlrev_b64 v[28:29], 13, v[28:29]
	v_lshl_add_u64 v[28:29], v[30:31], 0, v[28:29]
	global_load_dwordx4 v[28:31], v[28:29], off nt
	v_add_u32_e32 v53, v46, v47
	v_ashrrev_i32_e32 v57, 31, v56
	s_waitcnt vmcnt(7)
	ds_write2_b32 v53, v0, v1 offset1:1
	ds_write2_b32 v53, v2, v3 offset0:2 offset1:3
	v_add_u32_e32 v0, 0x420, v53
	s_waitcnt vmcnt(6)
	ds_write2_b32 v0, v4, v5 offset1:1
	v_add_u32_e32 v0, 0x428, v53
	ds_write2_b32 v0, v6, v7 offset1:1
	v_add_u32_e32 v0, 0x840, v53
	s_waitcnt vmcnt(5)
	ds_write2_b32 v0, v8, v9 offset1:1
	v_add_u32_e32 v0, 0x848, v53
	ds_write2_b32 v0, v10, v11 offset1:1
	v_add_u32_e32 v0, 0xc60, v53
	s_waitcnt vmcnt(4)
	ds_write2_b32 v0, v12, v13 offset1:1
	v_add_u32_e32 v0, 0xc68, v53
	ds_write2_b32 v0, v14, v15 offset1:1
	v_add_u32_e32 v0, 0x1080, v53
	s_waitcnt vmcnt(3)
	ds_write2_b32 v0, v16, v17 offset1:1
	v_add_u32_e32 v0, 0x1088, v53
	ds_write2_b32 v0, v18, v19 offset1:1
	v_add_u32_e32 v0, 0x14a0, v53
	s_waitcnt vmcnt(2)
	ds_write2_b32 v0, v20, v21 offset1:1
	v_add_u32_e32 v0, 0x14a8, v53
	ds_write2_b32 v0, v22, v23 offset1:1
	v_add_u32_e32 v0, 0x18c0, v53
	v_add_u32_e32 v22, v54, v45
	s_waitcnt vmcnt(1)
	ds_write2_b32 v0, v24, v25 offset1:1
	v_add_u32_e32 v0, 0x18c8, v53
	ds_write2_b32 v0, v26, v27 offset1:1
	v_add_u32_e32 v0, 0x1ce0, v53
	s_waitcnt vmcnt(0)
	ds_write2_b32 v0, v28, v29 offset1:1
	v_add_u32_e32 v0, 0x1ce8, v53
	ds_write2_b32 v0, v30, v31 offset1:1
	s_waitcnt lgkmcnt(0)
	ds_read2_b32 v[6:7], v51 offset0:33 offset1:41
	ds_read2_b32 v[8:9], v51 offset1:8
	ds_read2_b32 v[10:11], v51 offset0:66 offset1:74
	ds_read2_b32 v[12:13], v51 offset0:99 offset1:107
	ds_read2_b32 v[14:15], v51 offset0:132 offset1:140
	ds_read2_b32 v[16:17], v51 offset0:165 offset1:173
	ds_read2_b32 v[18:19], v51 offset0:198 offset1:206
	ds_read2_b32 v[20:21], v51 offset0:231 offset1:239
	v_ashrrev_i32_e32 v23, 31, v22
	v_lshl_add_u64 v[0:1], v[56:57], 1, v[42:43]
	v_lshlrev_b64 v[24:25], 12, v[22:23]
	s_waitcnt lgkmcnt(6)
	v_cvt_pk_bf16_f32 v2, v8, v6
	s_waitcnt lgkmcnt(4)
	v_cvt_pk_bf16_f32 v3, v10, v12
	s_waitcnt lgkmcnt(2)
	v_cvt_pk_bf16_f32 v4, v14, v16
	s_waitcnt lgkmcnt(0)
	v_cvt_pk_bf16_f32 v5, v18, v20
	v_lshl_add_u64 v[24:25], v[0:1], 0, v[24:25]
	v_add_u32_e32 v6, 8, v22
	global_store_dwordx4 v[24:25], v[2:5], off
	v_add_u32_e32 v24, 16, v22
	v_ashrrev_i32_e32 v25, 31, v24
	v_cvt_pk_bf16_f32 v2, v9, v7
	v_ashrrev_i32_e32 v7, 31, v6
	v_lshlrev_b64 v[6:7], 12, v[6:7]
	v_cvt_pk_bf16_f32 v3, v11, v13
	v_cvt_pk_bf16_f32 v4, v15, v17
	v_cvt_pk_bf16_f32 v5, v19, v21
	v_lshl_add_u64 v[6:7], v[0:1], 0, v[6:7]
	global_store_dwordx4 v[6:7], v[2:5], off
	ds_read2_b32 v[6:7], v51 offset0:49 offset1:57
	ds_read2_b32 v[8:9], v51 offset0:16 offset1:24
	ds_read2_b32 v[10:11], v51 offset0:82 offset1:90
	ds_read2_b32 v[12:13], v51 offset0:115 offset1:123
	ds_read2_b32 v[14:15], v51 offset0:148 offset1:156
	ds_read2_b32 v[16:17], v51 offset0:181 offset1:189
	ds_read2_b32 v[18:19], v51 offset0:214 offset1:222
	ds_read2_b32 v[20:21], v51 offset0:247 offset1:255
	v_lshlrev_b64 v[24:25], 12, v[24:25]
	s_waitcnt lgkmcnt(6)
	v_cvt_pk_bf16_f32 v2, v8, v6
	s_waitcnt lgkmcnt(4)
	v_cvt_pk_bf16_f32 v3, v10, v12
	s_waitcnt lgkmcnt(2)
	v_cvt_pk_bf16_f32 v4, v14, v16
	s_waitcnt lgkmcnt(0)
	v_cvt_pk_bf16_f32 v5, v18, v20
	v_lshl_add_u64 v[24:25], v[0:1], 0, v[24:25]
	v_add_u32_e32 v6, 24, v22
	global_store_dwordx4 v[24:25], v[2:5], off
	s_nop 1
	v_cvt_pk_bf16_f32 v2, v9, v7
	v_ashrrev_i32_e32 v7, 31, v6
	v_lshlrev_b64 v[6:7], 12, v[6:7]
	v_cvt_pk_bf16_f32 v3, v11, v13
	v_cvt_pk_bf16_f32 v4, v15, v17
	v_cvt_pk_bf16_f32 v5, v19, v21
	v_lshl_add_u64 v[0:1], v[0:1], 0, v[6:7]
	global_store_dwordx4 v[0:1], v[2:5], off
	s_waitcnt lgkmcnt(0)
	s_branch .LBB0_268

; DI void transpose_item(const float* W, int K, int Nsrc, int srccol, int nvalid, const float* ksc, bf16_t* WT, int dstrow, int k0, LAS float* scr, int lane) {
;     ...
;     for (int i = 0; i < 8; ++i) { const int kk = k0 + 8 * i + (lane >> 3);
;         v[i] = (4 * (lane & 7) < nvalid) ? *(const f32x4*)(W + (size_t)kk * Nsrc + srccol + 4 * (lane & 7)) : (f32x4){0.f, 0.f, 0.f, 0.f};
; DI void convert_weights(const Args& a, int l, int sets, bf16_t* dstWin, int gw, int NGW, LAS unsigned char* lds, const int tidx) {
;     ...
;         for (int r = gw; r < I_IN; r += NGW) { const int nblk = NPAD / 32, kb = r / nblk, nb = r % nblk; const int dn = 32 * nb, nv = dn < 6912 ? 32 : (dn == 6912 ? 12 : 0);
;             transpose_item(win, DM, INDIM, win_srccol(dn < 6924 ? dn : 0), nv, a.norm1_w + l * DM, dstWin, dn, 64 * kb, scr, lane); }
.LBB0_324:
	s_or_b64 exec, exec, s[4:5]
	s_movk_i32 s4, 0xd8
	v_cmp_gt_i32_e32 vcc, s4, v2
	v_cmp_eq_u32_e64 s[4:5], s4, v2
	v_lshlrev_b32_e32 v38, 6, v1
	s_and_b64 s[4:5], s[4:5], s[0:1]
	v_ashrrev_i32_e32 v1, 31, v0
	v_or_b32_e32 v28, v38, v33
	s_or_b64 s[10:11], vcc, s[4:5]
	v_lshl_add_u64 v[40:41], v[0:1], 2, v[34:35]
	v_mov_b32_e32 v0, 0
	v_mov_b32_e32 v1, 0
	v_mov_b32_e32 v2, 0
	v_mov_b32_e32 v3, 0
	s_and_saveexec_b64 s[4:5], s[10:11]
	s_cbranch_execz .LBB0_326
	s_movk_i32 s12, 0x6c30
	v_mad_i64_i32 v[0:1], s[12:13], v28, s12, v[40:41]
	global_load_dwordx4 v[0:3], v[0:1], off nt

; DI void transpose_item(const float* W, int K, int Nsrc, int srccol, int nvalid, const float* ksc, bf16_t* WT, int dstrow, int k0, LAS float* scr, int lane) {
;     ...
;     for (int i = 0; i < 8; ++i) { const int kk = k0 + 8 * i + (lane >> 3);
;         v[i] = (4 * (lane & 7) < nvalid) ? *(const f32x4*)(W + (size_t)kk * Nsrc + srccol + 4 * (lane & 7)) : (f32x4){0.f, 0.f, 0.f, 0.f};
.LBB0_328:
	v_or_b32_e32 v8, 8, v28
	v_mov_b32_e32 v4, 0
	v_mov_b32_e32 v5, 0
	v_mov_b32_e32 v6, 0
	v_mov_b32_e32 v7, 0
	s_and_saveexec_b64 s[12:13], s[10:11]
	s_cbranch_execz .LBB0_330
	s_movk_i32 s14, 0x6c30
	v_mad_i64_i32 v[4:5], s[14:15], v8, s14, v[40:41]
	global_load_dwordx4 v[4:7], v[4:5], off nt

; DI void transpose_item(const float* W, int K, int Nsrc, int srccol, int nvalid, const float* ksc, bf16_t* WT, int dstrow, int k0, LAS float* scr, int lane) {
;     ...
;     for (int i = 0; i < 8; ++i) { const int kk = k0 + 8 * i + (lane >> 3);
;         v[i] = (4 * (lane & 7) < nvalid) ? *(const f32x4*)(W + (size_t)kk * Nsrc + srccol + 4 * (lane & 7)) : (f32x4){0.f, 0.f, 0.f, 0.f};
.LBB0_332:
	v_or_b32_e32 v12, 16, v28
	v_mov_b32_e32 v8, 0
	v_mov_b32_e32 v9, 0
	v_mov_b32_e32 v10, 0
	v_mov_b32_e32 v11, 0
	s_and_saveexec_b64 s[12:13], s[10:11]
	s_cbranch_execz .LBB0_334
	s_movk_i32 s14, 0x6c30
	v_mad_i64_i32 v[8:9], s[14:15], v12, s14, v[40:41]
	global_load_dwordx4 v[8:11], v[8:9], off nt

; DI void transpose_item(const float* W, int K, int Nsrc, int srccol, int nvalid, const float* ksc, bf16_t* WT, int dstrow, int k0, LAS float* scr, int lane) {
;     ...
;     for (int i = 0; i < 8; ++i) { const int kk = k0 + 8 * i + (lane >> 3);
;         v[i] = (4 * (lane & 7) < nvalid) ? *(const f32x4*)(W + (size_t)kk * Nsrc + srccol + 4 * (lane & 7)) : (f32x4){0.f, 0.f, 0.f, 0.f};
.LBB0_336:
	v_or_b32_e32 v16, 24, v28
	v_mov_b32_e32 v12, 0
	v_mov_b32_e32 v13, 0
	v_mov_b32_e32 v14, 0
	v_mov_b32_e32 v15, 0
	s_and_saveexec_b64 s[12:13], s[10:11]
	s_cbranch_execz .LBB0_338
	s_movk_i32 s14, 0x6c30
	v_mad_i64_i32 v[12:13], s[14:15], v16, s14, v[40:41]
	global_load_dwordx4 v[12:15], v[12:13], off nt

; DI void transpose_item(const float* W, int K, int Nsrc, int srccol, int nvalid, const float* ksc, bf16_t* WT, int dstrow, int k0, LAS float* scr, int lane) {
;     ...
;     for (int i = 0; i < 8; ++i) { const int kk = k0 + 8 * i + (lane >> 3);
;         v[i] = (4 * (lane & 7) < nvalid) ? *(const f32x4*)(W + (size_t)kk * Nsrc + srccol + 4 * (lane & 7)) : (f32x4){0.f, 0.f, 0.f, 0.f};
.LBB0_340:
	v_or_b32_e32 v20, 32, v28
	v_mov_b32_e32 v16, 0
	v_mov_b32_e32 v17, 0
	v_mov_b32_e32 v18, 0
	v_mov_b32_e32 v19, 0
	s_and_saveexec_b64 s[12:13], s[10:11]
	s_cbranch_execz .LBB0_342
	s_movk_i32 s14, 0x6c30
	v_mad_i64_i32 v[16:17], s[14:15], v20, s14, v[40:41]
	global_load_dwordx4 v[16:19], v[16:17], off nt

; DI void transpose_item(const float* W, int K, int Nsrc, int srccol, int nvalid, const float* ksc, bf16_t* WT, int dstrow, int k0, LAS float* scr, int lane) {
;     ...
;     for (int i = 0; i < 8; ++i) { const int kk = k0 + 8 * i + (lane >> 3);
;         v[i] = (4 * (lane & 7) < nvalid) ? *(const f32x4*)(W + (size_t)kk * Nsrc + srccol + 4 * (lane & 7)) : (f32x4){0.f, 0.f, 0.f, 0.f};
.LBB0_344:
	v_or_b32_e32 v24, 40, v28
	v_mov_b32_e32 v20, 0
	v_mov_b32_e32 v21, 0
	v_mov_b32_e32 v22, 0
	v_mov_b32_e32 v23, 0
	s_and_saveexec_b64 s[12:13], s[10:11]
	s_cbranch_execz .LBB0_346
	s_movk_i32 s14, 0x6c30
	v_mad_i64_i32 v[20:21], s[14:15], v24, s14, v[40:41]
	global_load_dwordx4 v[20:23], v[20:21], off nt

; DI void transpose_item(const float* W, int K, int Nsrc, int srccol, int nvalid, const float* ksc, bf16_t* WT, int dstrow, int k0, LAS float* scr, int lane) {
;     ...
;     for (int i = 0; i < 8; ++i) { const int kk = k0 + 8 * i + (lane >> 3);
;         v[i] = (4 * (lane & 7) < nvalid) ? *(const f32x4*)(W + (size_t)kk * Nsrc + srccol + 4 * (lane & 7)) : (f32x4){0.f, 0.f, 0.f, 0.f};
.LBB0_348:
	v_or_b32_e32 v30, 48, v28
	v_mov_b32_e32 v24, 0
	v_mov_b32_e32 v25, 0
	v_mov_b32_e32 v26, 0
	v_mov_b32_e32 v27, 0
	s_and_saveexec_b64 s[12:13], s[10:11]
	s_cbranch_execz .LBB0_350
	s_movk_i32 s14, 0x6c30
	v_mad_i64_i32 v[24:25], s[14:15], v30, s14, v[40:41]
	global_load_dwordx4 v[24:27], v[24:25], off nt

; DI void transpose_item(const float* W, int K, int Nsrc, int srccol, int nvalid, const float* ksc, bf16_t* WT, int dstrow, int k0, LAS float* scr, int lane) {
;     ...
;     for (int i = 0; i < 8; ++i) { const int kk = k0 + 8 * i + (lane >> 3);
;         v[i] = (4 * (lane & 7) < nvalid) ? *(const f32x4*)(W + (size_t)kk * Nsrc + srccol + 4 * (lane & 7)) : (f32x4){0.f, 0.f, 0.f, 0.f};
.LBB0_352:
	v_or_b32_e32 v42, 56, v28
	v_mov_b32_e32 v28, 0
	v_mov_b32_e32 v29, 0
	v_mov_b32_e32 v30, 0
	v_mov_b32_e32 v31, 0
	s_and_saveexec_b64 s[12:13], s[10:11]
	s_cbranch_execz .LBB0_354
	s_movk_i32 s10, 0x6c30
	v_mad_i64_i32 v[28:29], s[10:11], v42, s10, v[40:41]
	global_load_dwordx4 v[28:31], v[28:29], off nt
